# v32: v28 + GU block 1 also two-pair interleaved (its row-scale pair reused as second temp after the scaling step); block 0 unchanged
# speedup vs baseline: 1.0031x; 1.0016x over previous
; #define PG8_LAS __attribute__((address_space(3)))
; __device__ __forceinline__ u32x4 pack8(const f32x4 a, const f32x4 b) { u32x4 w; w.x = cvt_pk_bf16(a[0], a[1]); w.y = cvt_pk_bf16(a[2], a[3]); w.z = cvt_pk_bf16(b[0], b[1]); w.w = cvt_pk_bf16(b[2], b[3]); return w; }
;     __device__ __forceinline__ void operator()(const f32x4 (&acc)[2][2][4][2], const Unit& u, int wr, int wc, int fr, int fq) const {
;         PG8_LAS const float* R = stage_rstd((const float*)(ws + WS_PS), lds, u.pm);
; #pragma unroll
;         for (int ai = 0; ai < 2; ++ai)
; #pragma unroll
;             for (int m = 0; m < 4; ++m) {
;                 const int row = u.pm * BM + ai * HALF + wr * 64 + m * 16 + fr;
;                 const float rs = R[ai * HALF + wr * 64 + m * 16 + fr];
;                 bf16_t* ACT = (bf16_t*)(ws + WS_ACT);
;                 f32x4 a[2];
; #pragma unroll
;                 for (int n = 0; n < 2; ++n) {
;                     const f32x4 g = acc[ai][0][m][n] * rs, uu = acc[ai][1][m][n] * rs;
; #pragma unroll
;                     for (int j = 0; j < 4; ++j) a[n][j] = g[j] * __builtin_amdgcn_rcpf(1.0f + __builtin_amdgcn_exp2f(-1.4426950408889634f * g[j])) * uu[j];
;                 }
;                 *(u32x4*)(ACT + (size_t)row * 2816 + u.pn * 128 + wc * 32 + 8 * fq) = pack8(a[0], a[1]);
;             }
.LBB0_38:
	s_lshl_b32 s3, s48, 8
	ds_read_b32 v146, v142
	v_mov_b32_e32 v145, 0xbfb8aa3b
	s_waitcnt lgkmcnt(0)
	v_pk_mul_f32 v[124:125], v[124:125], v[146:147] op_sel_hi:[1,0]
	v_pk_mul_f32 v[126:127], v[126:127], v[146:147] op_sel_hi:[1,0]
	v_pk_mul_f32 v[116:117], v[116:117], v[146:147] op_sel_hi:[1,0]
	v_pk_mul_f32 v[118:119], v[118:119], v[146:147] op_sel_hi:[1,0]
	v_pk_mul_f32 v[120:121], v[120:121], v[146:147] op_sel_hi:[1,0]
	v_pk_mul_f32 v[122:123], v[122:123], v[146:147] op_sel_hi:[1,0]
	v_pk_mul_f32 v[112:113], v[112:113], v[146:147] op_sel_hi:[1,0]
	v_pk_mul_f32 v[114:115], v[114:115], v[146:147] op_sel_hi:[1,0]
	v_pk_mul_f32 v[148:149], v[124:125], v[144:145] op_sel:[0,1] op_sel_hi:[1,1]
	v_exp_f32_e32 v148, v148
	v_exp_f32_e32 v149, v149
	v_add_f32_e32 v148, 1.0, v148
	v_add_f32_e32 v149, 1.0, v149
	v_rcp_f32_e32 v148, v148
	v_rcp_f32_e32 v149, v149
	s_nop 0
	v_pk_mul_f32 v[124:125], v[124:125], v[148:149]
	v_pk_mul_f32 v[120:121], v[120:121], v[124:125]
	v_pk_mul_f32 v[148:149], v[126:127], v[144:145] op_sel:[0,1] op_sel_hi:[1,1]
	v_exp_f32_e32 v148, v148
	v_exp_f32_e32 v149, v149
	v_add_f32_e32 v148, 1.0, v148
	v_add_f32_e32 v149, 1.0, v149
	v_rcp_f32_e32 v148, v148
	v_rcp_f32_e32 v149, v149
	s_nop 0
	v_pk_mul_f32 v[126:127], v[126:127], v[148:149]
	v_pk_mul_f32 v[122:123], v[122:123], v[126:127]
	v_pk_mul_f32 v[148:149], v[116:117], v[144:145] op_sel:[0,1] op_sel_hi:[1,1]
	v_exp_f32_e32 v148, v148
	v_exp_f32_e32 v149, v149
	v_add_f32_e32 v148, 1.0, v148
	v_add_f32_e32 v149, 1.0, v149
	v_rcp_f32_e32 v148, v148
	v_rcp_f32_e32 v149, v149
	s_nop 0
	v_pk_mul_f32 v[116:117], v[116:117], v[148:149]
	v_pk_mul_f32 v[112:113], v[112:113], v[116:117]
	v_pk_mul_f32 v[148:149], v[118:119], v[144:145] op_sel:[0,1] op_sel_hi:[1,1]
	v_exp_f32_e32 v148, v148
	v_exp_f32_e32 v149, v149
	v_add_f32_e32 v148, 1.0, v148
	v_add_f32_e32 v149, 1.0, v149
	v_rcp_f32_e32 v148, v148
	v_rcp_f32_e32 v149, v149
	s_nop 0
	v_pk_mul_f32 v[118:119], v[118:119], v[148:149]
	v_pk_mul_f32 v[114:115], v[114:115], v[118:119]
	v_cvt_pk_bf16_f32 v116, v112, v113
	v_cvt_pk_bf16_f32 v117, v114, v115
	v_cvt_pk_bf16_f32 v114, v120, v121
	v_cvt_pk_bf16_f32 v115, v122, v123
	s_lshl_b32 s0, s47, 7
	v_add_u32_e32 v144, s3, v140
	s_ashr_i32 s1, s0, 31
	s_movk_i32 s3, 0x1600
	s_lshl_b64 s[0:1], s[0:1], 1
	s_andn2_b64 vcc, exec, s[36:37]
	v_mov_b64_e32 v[112:113], s[16:17]
	s_mov_b32 s101, 0
	v_mad_i64_i32 v[118:119], s[4:5], v144, s3, v[112:113]
	v_lshl_add_u64 v[118:119], v[118:119], 0, s[0:1]
	v_lshl_add_u64 v[118:119], v[118:119], 0, s[34:35]
	v_lshl_add_u64 v[118:119], v[118:119], 0, v[184:185]
	global_store_dwordx4 v[118:119], v[114:117], off
	ds_read_b32 v114, v142 offset:64
	ds_read_b32 v120, v142 offset:128
	ds_read_b32 v122, v142 offset:192
	ds_read_b32 v124, v142 offset:512
	ds_read_b32 v126, v142 offset:576
	ds_read_b32 v112, v142 offset:640
	ds_read_b32 v116, v142 offset:704
	v_mov_b32_e32 v146, 1.0
	s_waitcnt lgkmcnt(6)
	v_pk_mul_f32 v[108:109], v[108:109], v[114:115] op_sel_hi:[1,0]
	v_pk_mul_f32 v[110:111], v[110:111], v[114:115] op_sel_hi:[1,0]
	v_pk_mul_f32 v[100:101], v[100:101], v[114:115] op_sel_hi:[1,0]
	v_pk_mul_f32 v[102:103], v[102:103], v[114:115] op_sel_hi:[1,0]
	v_pk_mul_f32 v[104:105], v[104:105], v[114:115] op_sel_hi:[1,0]
	v_pk_mul_f32 v[106:107], v[106:107], v[114:115] op_sel_hi:[1,0]
	v_pk_mul_f32 v[96:97], v[96:97], v[114:115] op_sel_hi:[1,0]
	v_pk_mul_f32 v[98:99], v[98:99], v[114:115] op_sel_hi:[1,0]
	v_pk_mul_f32 v[148:149], v[108:109], v[144:145] op_sel:[0,1] op_sel_hi:[1,1]
	v_pk_mul_f32 v[114:115], v[110:111], v[144:145] op_sel:[0,1] op_sel_hi:[1,1]
	v_exp_f32_e32 v148, v148
	v_exp_f32_e32 v149, v149
	v_exp_f32_e32 v114, v114
	v_exp_f32_e32 v115, v115
	v_pk_add_f32 v[148:149], v[148:149], v[146:147] op_sel_hi:[1,0]
	v_pk_add_f32 v[114:115], v[114:115], v[146:147] op_sel_hi:[1,0]
	v_rcp_f32_e32 v148, v148
	v_rcp_f32_e32 v149, v149
	v_rcp_f32_e32 v114, v114
	v_rcp_f32_e32 v115, v115
	v_pk_mul_f32 v[108:109], v[108:109], v[148:149]
	v_pk_mul_f32 v[110:111], v[110:111], v[114:115]
	v_pk_mul_f32 v[104:105], v[104:105], v[108:109]
	v_pk_mul_f32 v[106:107], v[106:107], v[110:111]
	v_pk_mul_f32 v[148:149], v[100:101], v[144:145] op_sel:[0,1] op_sel_hi:[1,1]
	v_pk_mul_f32 v[114:115], v[102:103], v[144:145] op_sel:[0,1] op_sel_hi:[1,1]
	v_exp_f32_e32 v148, v148
	v_exp_f32_e32 v149, v149
	v_exp_f32_e32 v114, v114
	v_exp_f32_e32 v115, v115
	v_pk_add_f32 v[148:149], v[148:149], v[146:147] op_sel_hi:[1,0]
	v_pk_add_f32 v[114:115], v[114:115], v[146:147] op_sel_hi:[1,0]
	v_rcp_f32_e32 v148, v148
	v_rcp_f32_e32 v149, v149
	v_rcp_f32_e32 v114, v114
	v_rcp_f32_e32 v115, v115
	v_pk_mul_f32 v[100:101], v[100:101], v[148:149]
	v_pk_mul_f32 v[102:103], v[102:103], v[114:115]
	v_pk_mul_f32 v[96:97], v[96:97], v[100:101]
	v_pk_mul_f32 v[98:99], v[98:99], v[102:103]
	v_cvt_pk_bf16_f32 v99, v98, v99
	v_cvt_pk_bf16_f32 v98, v96, v97
	v_cvt_pk_bf16_f32 v96, v104, v105
	v_cvt_pk_bf16_f32 v97, v106, v107
	s_mov_b32 s100, 0x16000
	v_lshl_add_u64 v[100:101], v[118:119], 0, s[100:101]
	global_store_dwordx4 v[100:101], v[96:99], off
	s_waitcnt lgkmcnt(0)
; __device__ __forceinline__ u32x4 pack8(const f32x4 a, const f32x4 b) { u32x4 w; w.x = cvt_pk_bf16(a[0], a[1]); w.y = cvt_pk_bf16(a[2], a[3]); w.z = cvt_pk_bf16(b[0], b[1]); w.w = cvt_pk_bf16(b[2], b[3]); return w; }
;     __device__ __forceinline__ void operator()(const f32x4 (&acc)[2][2][4][2], const Unit& u, int wr, int wc, int fr, int fq) const {
;     ...
;             for (int m = 0; m < 4; ++m) {
;                 const int row = u.pm * BM + ai * HALF + wr * 64 + m * 16 + fr;
;                 const float rs = R[ai * HALF + wr * 64 + m * 16 + fr];
;                 bf16_t* ACT = (bf16_t*)(ws + WS_ACT);
;                 f32x4 a[2];
; #pragma unroll
;                 for (int n = 0; n < 2; ++n) {
;                     const f32x4 g = acc[ai][0][m][n] * rs, uu = acc[ai][1][m][n] * rs;
; #pragma unroll
;                     for (int j = 0; j < 4; ++j) a[n][j] = g[j] * __builtin_amdgcn_rcpf(1.0f + __builtin_amdgcn_exp2f(-1.4426950408889634f * g[j])) * uu[j];
;                 }
;                 *(u32x4*)(ACT + (size_t)row * 2816 + u.pn * 128 + wc * 32 + 8 * fq) = pack8(a[0], a[1]);
;             }
	v_pk_mul_f32 v[92:93], v[92:93], v[120:121] op_sel_hi:[1,0]
	v_pk_mul_f32 v[94:95], v[94:95], v[120:121] op_sel_hi:[1,0]
	v_pk_mul_f32 v[84:85], v[84:85], v[120:121] op_sel_hi:[1,0]
	v_pk_mul_f32 v[86:87], v[86:87], v[120:121] op_sel_hi:[1,0]
	v_pk_mul_f32 v[88:89], v[88:89], v[120:121] op_sel_hi:[1,0]
	v_pk_mul_f32 v[90:91], v[90:91], v[120:121] op_sel_hi:[1,0]
	v_pk_mul_f32 v[80:81], v[80:81], v[120:121] op_sel_hi:[1,0]
	v_pk_mul_f32 v[82:83], v[82:83], v[120:121] op_sel_hi:[1,0]
	v_pk_mul_f32 v[148:149], v[92:93], v[144:145] op_sel:[0,1] op_sel_hi:[1,1]
	v_pk_mul_f32 v[114:115], v[94:95], v[144:145] op_sel:[0,1] op_sel_hi:[1,1]
	v_exp_f32_e32 v148, v148
	v_exp_f32_e32 v149, v149
	v_exp_f32_e32 v114, v114
	v_exp_f32_e32 v115, v115
	v_pk_add_f32 v[148:149], v[148:149], v[146:147] op_sel_hi:[1,0]
	v_pk_add_f32 v[114:115], v[114:115], v[146:147] op_sel_hi:[1,0]
	v_rcp_f32_e32 v148, v148
	v_rcp_f32_e32 v149, v149
	v_rcp_f32_e32 v114, v114
	v_rcp_f32_e32 v115, v115
	v_pk_mul_f32 v[92:93], v[92:93], v[148:149]
	v_pk_mul_f32 v[94:95], v[94:95], v[114:115]
	v_pk_mul_f32 v[88:89], v[88:89], v[92:93]
	v_pk_mul_f32 v[90:91], v[90:91], v[94:95]
	v_pk_mul_f32 v[148:149], v[84:85], v[144:145] op_sel:[0,1] op_sel_hi:[1,1]
	v_pk_mul_f32 v[114:115], v[86:87], v[144:145] op_sel:[0,1] op_sel_hi:[1,1]
	v_exp_f32_e32 v148, v148
	v_exp_f32_e32 v149, v149
	v_exp_f32_e32 v114, v114
	v_exp_f32_e32 v115, v115
	v_pk_add_f32 v[148:149], v[148:149], v[146:147] op_sel_hi:[1,0]
	v_pk_add_f32 v[114:115], v[114:115], v[146:147] op_sel_hi:[1,0]
	v_rcp_f32_e32 v148, v148
	v_rcp_f32_e32 v149, v149
	v_rcp_f32_e32 v114, v114
	v_rcp_f32_e32 v115, v115
	v_pk_mul_f32 v[84:85], v[84:85], v[148:149]
	v_pk_mul_f32 v[86:87], v[86:87], v[114:115]
	v_pk_mul_f32 v[80:81], v[80:81], v[84:85]
	v_pk_mul_f32 v[82:83], v[82:83], v[86:87]
	v_cvt_pk_bf16_f32 v83, v82, v83
	v_cvt_pk_bf16_f32 v82, v80, v81
	v_cvt_pk_bf16_f32 v80, v88, v89
	v_cvt_pk_bf16_f32 v81, v90, v91
	s_mov_b32 s100, 0x2c000
	v_lshl_add_u64 v[84:85], v[118:119], 0, s[100:101]
	global_store_dwordx4 v[84:85], v[80:83], off
	s_waitcnt lgkmcnt(0)
	v_pk_mul_f32 v[76:77], v[76:77], v[122:123] op_sel_hi:[1,0]
	v_pk_mul_f32 v[78:79], v[78:79], v[122:123] op_sel_hi:[1,0]
	v_pk_mul_f32 v[68:69], v[68:69], v[122:123] op_sel_hi:[1,0]
	v_pk_mul_f32 v[70:71], v[70:71], v[122:123] op_sel_hi:[1,0]
	v_pk_mul_f32 v[72:73], v[72:73], v[122:123] op_sel_hi:[1,0]
	v_pk_mul_f32 v[74:75], v[74:75], v[122:123] op_sel_hi:[1,0]
	v_pk_mul_f32 v[64:65], v[64:65], v[122:123] op_sel_hi:[1,0]
	v_pk_mul_f32 v[66:67], v[66:67], v[122:123] op_sel_hi:[1,0]
	v_pk_mul_f32 v[148:149], v[76:77], v[144:145] op_sel:[0,1] op_sel_hi:[1,1]
	v_pk_mul_f32 v[114:115], v[78:79], v[144:145] op_sel:[0,1] op_sel_hi:[1,1]
	v_exp_f32_e32 v148, v148
	v_exp_f32_e32 v149, v149
	v_exp_f32_e32 v114, v114
	v_exp_f32_e32 v115, v115
	v_pk_add_f32 v[148:149], v[148:149], v[146:147] op_sel_hi:[1,0]
	v_pk_add_f32 v[114:115], v[114:115], v[146:147] op_sel_hi:[1,0]
	v_rcp_f32_e32 v148, v148
	v_rcp_f32_e32 v149, v149
	v_rcp_f32_e32 v114, v114
	v_rcp_f32_e32 v115, v115
	v_pk_mul_f32 v[76:77], v[76:77], v[148:149]
	v_pk_mul_f32 v[78:79], v[78:79], v[114:115]
	v_pk_mul_f32 v[72:73], v[72:73], v[76:77]
	v_pk_mul_f32 v[74:75], v[74:75], v[78:79]
	v_pk_mul_f32 v[148:149], v[68:69], v[144:145] op_sel:[0,1] op_sel_hi:[1,1]
	v_pk_mul_f32 v[114:115], v[70:71], v[144:145] op_sel:[0,1] op_sel_hi:[1,1]
	v_exp_f32_e32 v148, v148
	v_exp_f32_e32 v149, v149
	v_exp_f32_e32 v114, v114
	v_exp_f32_e32 v115, v115
	v_pk_add_f32 v[148:149], v[148:149], v[146:147] op_sel_hi:[1,0]
	v_pk_add_f32 v[114:115], v[114:115], v[146:147] op_sel_hi:[1,0]
	v_rcp_f32_e32 v148, v148
	v_rcp_f32_e32 v149, v149
	v_rcp_f32_e32 v114, v114
	v_rcp_f32_e32 v115, v115
	v_pk_mul_f32 v[68:69], v[68:69], v[148:149]
	v_pk_mul_f32 v[70:71], v[70:71], v[114:115]
	v_pk_mul_f32 v[64:65], v[64:65], v[68:69]
	v_pk_mul_f32 v[66:67], v[66:67], v[70:71]
	v_cvt_pk_bf16_f32 v67, v66, v67
	v_cvt_pk_bf16_f32 v66, v64, v65
	v_cvt_pk_bf16_f32 v64, v72, v73
	v_cvt_pk_bf16_f32 v65, v74, v75
	s_mov_b32 s100, 0x42000
	v_lshl_add_u64 v[68:69], v[118:119], 0, s[100:101]
	global_store_dwordx4 v[68:69], v[64:67], off
	s_waitcnt lgkmcnt(0)
	v_pk_mul_f32 v[60:61], v[60:61], v[124:125] op_sel_hi:[1,0]
	v_pk_mul_f32 v[62:63], v[62:63], v[124:125] op_sel_hi:[1,0]
	v_pk_mul_f32 v[52:53], v[52:53], v[124:125] op_sel_hi:[1,0]
	v_pk_mul_f32 v[54:55], v[54:55], v[124:125] op_sel_hi:[1,0]
	v_pk_mul_f32 v[56:57], v[56:57], v[124:125] op_sel_hi:[1,0]
	v_pk_mul_f32 v[58:59], v[58:59], v[124:125] op_sel_hi:[1,0]
	v_pk_mul_f32 v[48:49], v[48:49], v[124:125] op_sel_hi:[1,0]
	v_pk_mul_f32 v[50:51], v[50:51], v[124:125] op_sel_hi:[1,0]
	v_pk_mul_f32 v[148:149], v[60:61], v[144:145] op_sel:[0,1] op_sel_hi:[1,1]
	v_pk_mul_f32 v[114:115], v[62:63], v[144:145] op_sel:[0,1] op_sel_hi:[1,1]
	v_exp_f32_e32 v148, v148
	v_exp_f32_e32 v149, v149
	v_exp_f32_e32 v114, v114
	v_exp_f32_e32 v115, v115
	v_pk_add_f32 v[148:149], v[148:149], v[146:147] op_sel_hi:[1,0]
	v_pk_add_f32 v[114:115], v[114:115], v[146:147] op_sel_hi:[1,0]
	v_rcp_f32_e32 v148, v148
	v_rcp_f32_e32 v149, v149
	v_rcp_f32_e32 v114, v114
	v_rcp_f32_e32 v115, v115
	v_pk_mul_f32 v[60:61], v[60:61], v[148:149]
	v_pk_mul_f32 v[62:63], v[62:63], v[114:115]
	v_pk_mul_f32 v[56:57], v[56:57], v[60:61]
	v_pk_mul_f32 v[58:59], v[58:59], v[62:63]
	v_pk_mul_f32 v[148:149], v[52:53], v[144:145] op_sel:[0,1] op_sel_hi:[1,1]
	v_pk_mul_f32 v[114:115], v[54:55], v[144:145] op_sel:[0,1] op_sel_hi:[1,1]
	v_exp_f32_e32 v148, v148
	v_exp_f32_e32 v149, v149
	v_exp_f32_e32 v114, v114
	v_exp_f32_e32 v115, v115
	v_pk_add_f32 v[148:149], v[148:149], v[146:147] op_sel_hi:[1,0]
	v_pk_add_f32 v[114:115], v[114:115], v[146:147] op_sel_hi:[1,0]
	v_rcp_f32_e32 v148, v148
	v_rcp_f32_e32 v149, v149
	v_rcp_f32_e32 v114, v114
	v_rcp_f32_e32 v115, v115
	v_pk_mul_f32 v[52:53], v[52:53], v[148:149]
	v_pk_mul_f32 v[54:55], v[54:55], v[114:115]
	v_pk_mul_f32 v[48:49], v[48:49], v[52:53]
	v_pk_mul_f32 v[50:51], v[50:51], v[54:55]
	v_cvt_pk_bf16_f32 v51, v50, v51
	v_cvt_pk_bf16_f32 v50, v48, v49
	v_cvt_pk_bf16_f32 v48, v56, v57
	v_cvt_pk_bf16_f32 v49, v58, v59
	s_mov_b32 s100, 0xb0000
	v_lshl_add_u64 v[52:53], v[118:119], 0, s[100:101]
	global_store_dwordx4 v[52:53], v[48:51], off
	s_waitcnt lgkmcnt(0)
; __device__ __forceinline__ u32x4 pack8(const f32x4 a, const f32x4 b) { u32x4 w; w.x = cvt_pk_bf16(a[0], a[1]); w.y = cvt_pk_bf16(a[2], a[3]); w.z = cvt_pk_bf16(b[0], b[1]); w.w = cvt_pk_bf16(b[2], b[3]); return w; }
;     __device__ __forceinline__ void operator()(const f32x4 (&acc)[2][2][4][2], const Unit& u, int wr, int wc, int fr, int fq) const {
;     ...
;             for (int m = 0; m < 4; ++m) {
;                 const int row = u.pm * BM + ai * HALF + wr * 64 + m * 16 + fr;
;                 const float rs = R[ai * HALF + wr * 64 + m * 16 + fr];
;                 bf16_t* ACT = (bf16_t*)(ws + WS_ACT);
;                 f32x4 a[2];
; #pragma unroll
;                 for (int n = 0; n < 2; ++n) {
;                     const f32x4 g = acc[ai][0][m][n] * rs, uu = acc[ai][1][m][n] * rs;
; #pragma unroll
;                     for (int j = 0; j < 4; ++j) a[n][j] = g[j] * __builtin_amdgcn_rcpf(1.0f + __builtin_amdgcn_exp2f(-1.4426950408889634f * g[j])) * uu[j];
;                 }
;                 *(u32x4*)(ACT + (size_t)row * 2816 + u.pn * 128 + wc * 32 + 8 * fq) = pack8(a[0], a[1]);
;             }
	v_pk_mul_f32 v[44:45], v[44:45], v[126:127] op_sel_hi:[1,0]
	v_pk_mul_f32 v[46:47], v[46:47], v[126:127] op_sel_hi:[1,0]
	v_pk_mul_f32 v[36:37], v[36:37], v[126:127] op_sel_hi:[1,0]
	v_pk_mul_f32 v[38:39], v[38:39], v[126:127] op_sel_hi:[1,0]
	v_pk_mul_f32 v[40:41], v[40:41], v[126:127] op_sel_hi:[1,0]
	v_pk_mul_f32 v[42:43], v[42:43], v[126:127] op_sel_hi:[1,0]
	v_pk_mul_f32 v[32:33], v[32:33], v[126:127] op_sel_hi:[1,0]
	v_pk_mul_f32 v[34:35], v[34:35], v[126:127] op_sel_hi:[1,0]
	v_pk_mul_f32 v[148:149], v[44:45], v[144:145] op_sel:[0,1] op_sel_hi:[1,1]
	v_pk_mul_f32 v[114:115], v[46:47], v[144:145] op_sel:[0,1] op_sel_hi:[1,1]
	v_exp_f32_e32 v148, v148
	v_exp_f32_e32 v149, v149
	v_exp_f32_e32 v114, v114
	v_exp_f32_e32 v115, v115
	v_pk_add_f32 v[148:149], v[148:149], v[146:147] op_sel_hi:[1,0]
	v_pk_add_f32 v[114:115], v[114:115], v[146:147] op_sel_hi:[1,0]
	v_rcp_f32_e32 v148, v148
	v_rcp_f32_e32 v149, v149
	v_rcp_f32_e32 v114, v114
	v_rcp_f32_e32 v115, v115
	v_pk_mul_f32 v[44:45], v[44:45], v[148:149]
	v_pk_mul_f32 v[46:47], v[46:47], v[114:115]
	v_pk_mul_f32 v[40:41], v[40:41], v[44:45]
	v_pk_mul_f32 v[42:43], v[42:43], v[46:47]
	v_pk_mul_f32 v[148:149], v[36:37], v[144:145] op_sel:[0,1] op_sel_hi:[1,1]
	v_pk_mul_f32 v[114:115], v[38:39], v[144:145] op_sel:[0,1] op_sel_hi:[1,1]
	v_exp_f32_e32 v148, v148
	v_exp_f32_e32 v149, v149
	v_exp_f32_e32 v114, v114
	v_exp_f32_e32 v115, v115
	v_pk_add_f32 v[148:149], v[148:149], v[146:147] op_sel_hi:[1,0]
	v_pk_add_f32 v[114:115], v[114:115], v[146:147] op_sel_hi:[1,0]
	v_rcp_f32_e32 v148, v148
	v_rcp_f32_e32 v149, v149
	v_rcp_f32_e32 v114, v114
	v_rcp_f32_e32 v115, v115
	v_pk_mul_f32 v[36:37], v[36:37], v[148:149]
	v_pk_mul_f32 v[38:39], v[38:39], v[114:115]
	v_pk_mul_f32 v[32:33], v[32:33], v[36:37]
	v_pk_mul_f32 v[34:35], v[34:35], v[38:39]
	v_cvt_pk_bf16_f32 v35, v34, v35
	v_cvt_pk_bf16_f32 v34, v32, v33
	v_cvt_pk_bf16_f32 v32, v40, v41
	v_cvt_pk_bf16_f32 v33, v42, v43
	s_mov_b32 s100, 0xc6000
	v_lshl_add_u64 v[36:37], v[118:119], 0, s[100:101]
	global_store_dwordx4 v[36:37], v[32:35], off
	s_waitcnt lgkmcnt(0)
	v_pk_mul_f32 v[28:29], v[28:29], v[112:113] op_sel_hi:[1,0]
	v_pk_mul_f32 v[30:31], v[30:31], v[112:113] op_sel_hi:[1,0]
	v_pk_mul_f32 v[20:21], v[20:21], v[112:113] op_sel_hi:[1,0]
	v_pk_mul_f32 v[22:23], v[22:23], v[112:113] op_sel_hi:[1,0]
	v_pk_mul_f32 v[24:25], v[24:25], v[112:113] op_sel_hi:[1,0]
	v_pk_mul_f32 v[26:27], v[26:27], v[112:113] op_sel_hi:[1,0]
	v_pk_mul_f32 v[16:17], v[16:17], v[112:113] op_sel_hi:[1,0]
	v_pk_mul_f32 v[18:19], v[18:19], v[112:113] op_sel_hi:[1,0]
	v_pk_mul_f32 v[148:149], v[28:29], v[144:145] op_sel:[0,1] op_sel_hi:[1,1]
	v_pk_mul_f32 v[114:115], v[30:31], v[144:145] op_sel:[0,1] op_sel_hi:[1,1]
	v_exp_f32_e32 v148, v148
	v_exp_f32_e32 v149, v149
	v_exp_f32_e32 v114, v114
	v_exp_f32_e32 v115, v115
	v_pk_add_f32 v[148:149], v[148:149], v[146:147] op_sel_hi:[1,0]
	v_pk_add_f32 v[114:115], v[114:115], v[146:147] op_sel_hi:[1,0]
	v_rcp_f32_e32 v148, v148
	v_rcp_f32_e32 v149, v149
	v_rcp_f32_e32 v114, v114
	v_rcp_f32_e32 v115, v115
	v_pk_mul_f32 v[28:29], v[28:29], v[148:149]
	v_pk_mul_f32 v[30:31], v[30:31], v[114:115]
	v_pk_mul_f32 v[24:25], v[24:25], v[28:29]
	v_pk_mul_f32 v[26:27], v[26:27], v[30:31]
	v_pk_mul_f32 v[148:149], v[20:21], v[144:145] op_sel:[0,1] op_sel_hi:[1,1]
	v_pk_mul_f32 v[114:115], v[22:23], v[144:145] op_sel:[0,1] op_sel_hi:[1,1]
	v_exp_f32_e32 v148, v148
	v_exp_f32_e32 v149, v149
	v_exp_f32_e32 v114, v114
	v_exp_f32_e32 v115, v115
	v_pk_add_f32 v[148:149], v[148:149], v[146:147] op_sel_hi:[1,0]
	v_pk_add_f32 v[114:115], v[114:115], v[146:147] op_sel_hi:[1,0]
	v_rcp_f32_e32 v148, v148
	v_rcp_f32_e32 v149, v149
	v_rcp_f32_e32 v114, v114
	v_rcp_f32_e32 v115, v115
	v_pk_mul_f32 v[20:21], v[20:21], v[148:149]
	v_pk_mul_f32 v[22:23], v[22:23], v[114:115]
	v_pk_mul_f32 v[16:17], v[16:17], v[20:21]
	v_pk_mul_f32 v[18:19], v[18:19], v[22:23]
	v_cvt_pk_bf16_f32 v19, v18, v19
	v_cvt_pk_bf16_f32 v18, v16, v17
	v_cvt_pk_bf16_f32 v16, v24, v25
	v_cvt_pk_bf16_f32 v17, v26, v27
	s_mov_b32 s100, 0xdc000
	v_lshl_add_u64 v[20:21], v[118:119], 0, s[100:101]
	global_store_dwordx4 v[20:21], v[16:19], off
	s_waitcnt lgkmcnt(0)
	v_pk_mul_f32 v[12:13], v[12:13], v[116:117] op_sel_hi:[1,0]
	v_pk_mul_f32 v[14:15], v[14:15], v[116:117] op_sel_hi:[1,0]
	v_pk_mul_f32 v[4:5], v[4:5], v[116:117] op_sel_hi:[1,0]
	v_pk_mul_f32 v[6:7], v[6:7], v[116:117] op_sel_hi:[1,0]
	v_pk_mul_f32 v[8:9], v[8:9], v[116:117] op_sel_hi:[1,0]
	v_pk_mul_f32 v[10:11], v[10:11], v[116:117] op_sel_hi:[1,0]
	v_pk_mul_f32 v[0:1], v[0:1], v[116:117] op_sel_hi:[1,0]
	v_pk_mul_f32 v[2:3], v[2:3], v[116:117] op_sel_hi:[1,0]
	v_pk_mul_f32 v[148:149], v[12:13], v[144:145] op_sel:[0,1] op_sel_hi:[1,1]
	v_pk_mul_f32 v[114:115], v[14:15], v[144:145] op_sel:[0,1] op_sel_hi:[1,1]
	v_exp_f32_e32 v148, v148
	v_exp_f32_e32 v149, v149
	v_exp_f32_e32 v114, v114
	v_exp_f32_e32 v115, v115
	v_pk_add_f32 v[148:149], v[148:149], v[146:147] op_sel_hi:[1,0]
	v_pk_add_f32 v[114:115], v[114:115], v[146:147] op_sel_hi:[1,0]
	v_rcp_f32_e32 v148, v148
	v_rcp_f32_e32 v149, v149
	v_rcp_f32_e32 v114, v114
	v_rcp_f32_e32 v115, v115
	v_pk_mul_f32 v[12:13], v[12:13], v[148:149]
	v_pk_mul_f32 v[14:15], v[14:15], v[114:115]
	v_pk_mul_f32 v[8:9], v[8:9], v[12:13]
	v_pk_mul_f32 v[10:11], v[10:11], v[14:15]
	v_pk_mul_f32 v[148:149], v[4:5], v[144:145] op_sel:[0,1] op_sel_hi:[1,1]
	v_pk_mul_f32 v[114:115], v[6:7], v[144:145] op_sel:[0,1] op_sel_hi:[1,1]
	v_exp_f32_e32 v148, v148
	v_exp_f32_e32 v149, v149
	v_exp_f32_e32 v114, v114
	v_exp_f32_e32 v115, v115
	v_pk_add_f32 v[148:149], v[148:149], v[146:147] op_sel_hi:[1,0]
	v_pk_add_f32 v[114:115], v[114:115], v[146:147] op_sel_hi:[1,0]
	v_rcp_f32_e32 v148, v148
	v_rcp_f32_e32 v149, v149
	v_rcp_f32_e32 v114, v114
	v_rcp_f32_e32 v115, v115
	v_pk_mul_f32 v[4:5], v[4:5], v[148:149]
	v_pk_mul_f32 v[6:7], v[6:7], v[114:115]
	v_pk_mul_f32 v[0:1], v[0:1], v[4:5]
	v_pk_mul_f32 v[2:3], v[2:3], v[6:7]
	v_cvt_pk_bf16_f32 v3, v2, v3
	v_cvt_pk_bf16_f32 v2, v0, v1
	v_cvt_pk_bf16_f32 v0, v8, v9
	v_cvt_pk_bf16_f32 v1, v10, v11
	s_mov_b32 s100, 0xf2000
	v_lshl_add_u64 v[4:5], v[118:119], 0, s[100:101]
	s_mov_b64 s[0:1], -1
	global_store_dwordx4 v[4:5], v[0:3], off
	s_cbranch_vccnz .LBB0_31
	s_andn2_b64 vcc, exec, s[8:9]
	s_cbranch_vccnz .LBB0_30
	s_barrier
	s_branch .LBB0_30
